# attention key loop unrolled x2 with score/probability register roles swapped between halves: removes 14 register-copy instructions per key block
# baseline (speedup 1.0000x reference)
.LBB0_1324:
	s_barrier
	s_add_i32 s73, s50, 3
	s_cmp_ge_u32 s73, s71
	s_cbranch_scc1 .LBB0_1326
	s_mul_hi_u32 s34, s50, 0xaaaaaaab
	s_lshr_b32 s34, s34, 1
	s_mul_i32 s34, s34, 0xc000
	s_sub_i32 s34, s31, s34
	s_add_i32 s34, s36, s34
	s_add_i32 s34, s2, s34
	s_lshl_b32 s35, s37, 14
	s_add_i32 s35, s76, s35
	s_mov_b32 m0, s34
	s_add_i32 s50, s35, 0xc000
	global_load_lds_dwordx4 v[114:115], off
	v_lshl_add_u64 v[192:193], v[114:115], 0, s[44:45]
	s_add_i32 m0, s34, 0x2000
	s_nop 0
	global_load_lds_dwordx4 v[192:193], off
	s_mov_b32 m0, s50
	s_nop 0
	global_load_lds_dwordx4 v[118:119], off
	s_add_i32 m0, s35, 0xe000
	s_nop 0
	global_load_lds_dwordx4 v[116:117], off
.LBB0_1326:
	s_mul_hi_u32 s34, s77, 0xaaaaaaab
	s_lshr_b32 s34, s34, 1
	s_mul_i32 s34, s34, 0xc000
	v_subrev_u32_e32 v0, s34, v130
	s_add_i32 s34, s2, s36
	v_add_u32_e32 v0, s34, v0
	ds_read_b128 v[188:191], v0
	ds_read_b128 v[82:85], v0 offset:4096
	ds_read_b128 v[94:97], v0 offset:6144
	ds_read_b128 v[98:101], v0 offset:1024
	ds_read_b128 v[86:89], v0 offset:2048
	ds_read_b128 v[132:135], v0 offset:3072
	s_lshl_b32 s34, s49, 14
	v_add_u32_e32 v131, s34, v124
	s_waitcnt lgkmcnt(5)
	v_mfma_f32_16x16x32_bf16 v[188:191], v[188:191], v[10:13], v[150:153]
	ds_read_b128 v[78:81], v0 offset:5120
	s_waitcnt lgkmcnt(2)
	v_mfma_f32_16x16x32_bf16 v[136:139], v[86:89], v[10:13], v[150:153]
	v_max3_f32 v102, v74, v75, v76
	v_max3_f32 v102, v102, v77, v70
	v_max3_f32 v102, v102, v71, v72
	v_max_f32_e32 v102, v102, v73
	ds_read_b128 v[86:89], v0 offset:7168
	v_mfma_f32_16x16x32_bf16 v[90:93], v[82:85], v[10:13], v[150:153]
	v_mfma_f32_16x16x32_bf16 v[94:97], v[94:97], v[10:13], v[150:153]
	ds_read_b128 v[82:85], v131 offset:49152
	v_max3_f32 v0, v22, v23, v24
	v_max3_f32 v0, v0, v25, v26
	v_max3_f32 v0, v0, v27, v28
	v_max3_f32 v0, v0, v29, v102
	ds_read_b128 v[102:105], v131 offset:51200
	v_mfma_f32_16x16x32_bf16 v[160:163], v[98:101], v[18:21], v[188:191]
	s_waitcnt lgkmcnt(4)
	v_mfma_f32_16x16x32_bf16 v[164:167], v[132:135], v[18:21], v[136:139]
	v_mov_b32_e32 v132, v0
	s_nop 1
	v_permlane16_swap_b32_e32 v0, v132
	v_max_f32_e32 v0, v0, v132
	v_mov_b32_e32 v132, v0
	s_nop 1
	v_permlane32_swap_b32_e32 v0, v132
	ds_read_b128 v[98:101], v131 offset:53248
	v_max_f32_e32 v0, v0, v132
	s_mov_b32 s34, 0x41000000
	v_cmp_lt_f32_e32 vcc, s34, v0
	s_cmp_lg_u64 vcc, 0
	s_cselect_b64 s[34:35], -1, 0
	s_cbranch_vccz .LBB0_1328
	v_cndmask_b32_e32 v132, 0, v0, vcc
	v_exp_f32_e64 v0, -v132
	v_sub_f32_e32 v74, v74, v132
	v_sub_f32_e32 v75, v75, v132
	v_sub_f32_e32 v76, v76, v132
	v_sub_f32_e32 v77, v77, v132
	v_sub_f32_e32 v70, v70, v132
	v_sub_f32_e32 v71, v71, v132
	v_sub_f32_e32 v72, v72, v132
	v_sub_f32_e32 v73, v73, v132
	v_sub_f32_e32 v22, v22, v132
	v_sub_f32_e32 v23, v23, v132
	v_sub_f32_e32 v24, v24, v132
	v_sub_f32_e32 v25, v25, v132
	v_sub_f32_e32 v26, v26, v132
	v_sub_f32_e32 v27, v27, v132
	v_sub_f32_e32 v28, v28, v132
	v_sub_f32_e32 v29, v29, v132
	v_add_f32_e32 v113, v113, v132
	v_xor_b32_e32 v150, 0x80000000, v113
	v_mov_b32_e32 v151, v150
	v_mov_b32_e32 v152, v150
	v_mov_b32_e32 v153, v150
	s_branch .LBB0_1329
.LBB0_1328:
.LBB0_1329:
	ds_read_b128 v[134:137], v131 offset:55296
	s_waitcnt lgkmcnt(5)
	v_mfma_f32_16x16x32_bf16 v[168:171], v[78:81], v[18:21], v[90:93]
	ds_read_b128 v[78:81], v131 offset:57344
	s_waitcnt lgkmcnt(5)
	v_mfma_f32_16x16x32_bf16 v[172:175], v[86:89], v[18:21], v[94:97]
	ds_read_b128 v[86:89], v131 offset:59392
	s_waitcnt lgkmcnt(5)
	v_mfma_f32_16x16x32_bf16 v[30:33], v[82:85], v[14:17], v[30:33]
	v_exp_f32_e32 v145, v74
	v_exp_f32_e32 v146, v75
	v_exp_f32_e32 v147, v76
	v_exp_f32_e32 v148, v77
	ds_read_b128 v[176:179], v131 offset:61440
	s_waitcnt lgkmcnt(5)
	v_mfma_f32_16x16x32_bf16 v[50:53], v[102:105], v[14:17], v[50:53]
	ds_read_b128 v[82:85], v131 offset:63488
	s_waitcnt lgkmcnt(5)
	v_mfma_f32_16x16x32_bf16 v[42:45], v[98:101], v[14:17], v[42:45]
	ds_read_b128 v[90:93], v131 offset:50176
	s_waitcnt lgkmcnt(5)
	v_mfma_f32_16x16x32_bf16 v[34:37], v[134:137], v[14:17], v[34:37]
	v_exp_f32_e32 v98, v70
	v_exp_f32_e32 v99, v71
	v_exp_f32_e32 v100, v72
	v_exp_f32_e32 v101, v73
	ds_read_b128 v[180:183], v131 offset:52224
	s_waitcnt lgkmcnt(5)
	v_mfma_f32_16x16x32_bf16 v[58:61], v[78:81], v[14:17], v[58:61]
	ds_read_b128 v[78:81], v131 offset:54272
	s_waitcnt lgkmcnt(5)
	v_mfma_f32_16x16x32_bf16 v[54:57], v[86:89], v[14:17], v[54:57]
	ds_read_b128 v[86:89], v131 offset:56320
	s_waitcnt lgkmcnt(5)
	v_mfma_f32_16x16x32_bf16 v[46:49], v[176:179], v[14:17], v[46:49]
	v_exp_f32_e32 v102, v22
	v_exp_f32_e32 v103, v23
	v_exp_f32_e32 v104, v24
	v_exp_f32_e32 v105, v25
	ds_read_b128 v[176:179], v131 offset:58368
	s_waitcnt lgkmcnt(5)
	v_mfma_f32_16x16x32_bf16 v[38:41], v[82:85], v[14:17], v[38:41]
	v_mfma_f32_16x16x32_bf16 v[2:5], v[154:157], v[14:17], v[2:5]
	ds_read_b128 v[94:97], v131 offset:60416
	s_waitcnt lgkmcnt(5)
	v_mfma_f32_16x16x32_bf16 v[30:33], v[90:93], v[6:9], v[30:33]
	v_exp_f32_e32 v133, v26
	v_exp_f32_e32 v134, v27
	v_exp_f32_e32 v135, v28
	v_exp_f32_e32 v136, v29
	ds_read_b128 v[90:93], v131 offset:62464
	s_waitcnt lgkmcnt(5)
	v_mfma_f32_16x16x32_bf16 v[50:53], v[180:183], v[6:9], v[50:53]
	ds_read_b128 v[180:183], v131 offset:64512
	s_waitcnt lgkmcnt(5)
	v_mfma_f32_16x16x32_bf16 v[42:45], v[78:81], v[6:9], v[42:45]
	s_waitcnt lgkmcnt(4)
	v_mfma_f32_16x16x32_bf16 v[34:37], v[86:89], v[6:9], v[34:37]
	v_cvt_pk_bf16_f32 v14, v145, v146
	v_cvt_pk_bf16_f32 v15, v147, v148
	v_cvt_pk_bf16_f32 v16, v98, v99
	v_cvt_pk_bf16_f32 v17, v100, v101
	v_cvt_pk_bf16_f32 v184, v102, v103
	v_cvt_pk_bf16_f32 v185, v104, v105
	v_cvt_pk_bf16_f32 v186, v133, v134
	v_cvt_pk_bf16_f32 v187, v135, v136
	s_waitcnt lgkmcnt(3)
	v_mfma_f32_16x16x32_bf16 v[58:61], v[176:179], v[6:9], v[58:61]
	s_waitcnt lgkmcnt(2)
	v_mfma_f32_16x16x32_bf16 v[54:57], v[94:97], v[6:9], v[54:57]
	s_waitcnt lgkmcnt(1)
	v_mfma_f32_16x16x32_bf16 v[46:49], v[90:93], v[6:9], v[46:49]
	s_waitcnt lgkmcnt(0)
	v_mfma_f32_16x16x32_bf16 v[38:41], v[180:183], v[6:9], v[38:41]
	v_mfma_f32_16x16x32_bf16 v[2:5], v[154:157], v[6:9], v[2:5]
	s_andn2_b64 vcc, exec, s[34:35]
	s_cbranch_vccnz .LBB0_1331
	v_sub_f32_e32 v160, v160, v132
	v_sub_f32_e32 v161, v161, v132
	v_sub_f32_e32 v162, v162, v132
	v_sub_f32_e32 v163, v163, v132
	v_sub_f32_e32 v164, v164, v132
	v_sub_f32_e32 v165, v165, v132
	v_sub_f32_e32 v166, v166, v132
	v_sub_f32_e32 v167, v167, v132
	v_sub_f32_e32 v168, v168, v132
	v_sub_f32_e32 v169, v169, v132
	v_sub_f32_e32 v170, v170, v132
	v_sub_f32_e32 v171, v171, v132
	v_sub_f32_e32 v172, v172, v132
	v_sub_f32_e32 v173, v173, v132
	v_sub_f32_e32 v174, v174, v132
	v_sub_f32_e32 v175, v175, v132
	v_pk_mul_f32 v[40:41], v[0:1], v[40:41] op_sel_hi:[0,1]
	v_pk_mul_f32 v[48:49], v[0:1], v[48:49] op_sel_hi:[0,1]
	v_pk_mul_f32 v[56:57], v[0:1], v[56:57] op_sel_hi:[0,1]
	v_pk_mul_f32 v[60:61], v[0:1], v[60:61] op_sel_hi:[0,1]
	v_pk_mul_f32 v[36:37], v[0:1], v[36:37] op_sel_hi:[0,1]
	v_pk_mul_f32 v[44:45], v[0:1], v[44:45] op_sel_hi:[0,1]
	v_pk_mul_f32 v[52:53], v[0:1], v[52:53] op_sel_hi:[0,1]
	v_pk_mul_f32 v[32:33], v[0:1], v[32:33] op_sel_hi:[0,1]
	v_pk_mul_f32 v[38:39], v[0:1], v[38:39] op_sel_hi:[0,1]
	v_pk_mul_f32 v[46:47], v[0:1], v[46:47] op_sel_hi:[0,1]
	v_pk_mul_f32 v[54:55], v[0:1], v[54:55] op_sel_hi:[0,1]
	v_pk_mul_f32 v[58:59], v[0:1], v[58:59] op_sel_hi:[0,1]
	v_pk_mul_f32 v[34:35], v[0:1], v[34:35] op_sel_hi:[0,1]
	v_pk_mul_f32 v[42:43], v[0:1], v[42:43] op_sel_hi:[0,1]
	v_pk_mul_f32 v[50:51], v[0:1], v[50:51] op_sel_hi:[0,1]
	v_pk_mul_f32 v[30:31], v[0:1], v[30:31] op_sel_hi:[0,1]
	v_pk_mul_f32 v[4:5], v[0:1], v[4:5] op_sel_hi:[0,1]
	v_pk_mul_f32 v[2:3], v[0:1], v[2:3] op_sel_hi:[0,1]
.LBB0_1331:
	s_add_i32 s34, s72, 1
	s_cmp_lg_u32 s72, 4
	s_cselect_b32 s34, s34, 0
	s_add_i32 s35, s37, 1
	s_cmp_lg_u32 s37, 4
	s_cselect_b32 s37, s35, 0
	s_addk_i32 s36, 0x4000
	s_add_i32 s77, s77, 1
	s_add_i32 s50, s73, -2
	v_lshl_add_u64 v[114:115], v[114:115], 0, s[74:75]
	v_lshl_add_u64 v[116:117], v[116:117], 0, s[44:45]
	s_cmp_eq_u32 s50, s71
	v_lshl_add_u64 v[118:119], v[118:119], 0, s[44:45]
	s_cbranch_scc1 .Latt_exitA
	s_mov_b32 s49, s72
	s_mov_b32 s72, s34
	s_cmp_ge_u32 s50, s0
	s_mov_b64 s[34:35], -1
	s_cbranch_scc1 .Latt_B_1321
	s_branch .Latt_B_1322

.Latt_B_1326:
	s_mul_hi_u32 s34, s77, 0xaaaaaaab
	s_lshr_b32 s34, s34, 1
	s_mul_i32 s34, s34, 0xc000
	v_subrev_u32_e32 v0, s34, v130
	s_add_i32 s34, s2, s36
	v_add_u32_e32 v0, s34, v0
	ds_read_b128 v[188:191], v0
	ds_read_b128 v[82:85], v0 offset:4096
	ds_read_b128 v[94:97], v0 offset:6144
	ds_read_b128 v[98:101], v0 offset:1024
	ds_read_b128 v[86:89], v0 offset:2048
	ds_read_b128 v[132:135], v0 offset:3072
	s_lshl_b32 s34, s49, 14
	v_add_u32_e32 v131, s34, v124
	s_waitcnt lgkmcnt(5)
	v_mfma_f32_16x16x32_bf16 v[188:191], v[188:191], v[10:13], v[150:153]
	ds_read_b128 v[78:81], v0 offset:5120
	s_waitcnt lgkmcnt(2)
	v_mfma_f32_16x16x32_bf16 v[136:139], v[86:89], v[10:13], v[150:153]
	v_max3_f32 v102, v160, v161, v162
	v_max3_f32 v102, v102, v163, v164
	v_max3_f32 v102, v102, v165, v166
	v_max_f32_e32 v102, v102, v167
	ds_read_b128 v[86:89], v0 offset:7168
	v_mfma_f32_16x16x32_bf16 v[90:93], v[82:85], v[10:13], v[150:153]
	v_mfma_f32_16x16x32_bf16 v[94:97], v[94:97], v[10:13], v[150:153]
	ds_read_b128 v[82:85], v131 offset:49152
	v_max3_f32 v0, v168, v169, v170
	v_max3_f32 v0, v0, v171, v172
	v_max3_f32 v0, v0, v173, v174
	v_max3_f32 v0, v0, v175, v102
	ds_read_b128 v[102:105], v131 offset:51200
	v_mfma_f32_16x16x32_bf16 v[74:77], v[98:101], v[18:21], v[188:191]
	s_waitcnt lgkmcnt(4)
	v_mfma_f32_16x16x32_bf16 v[70:73], v[132:135], v[18:21], v[136:139]
	v_mov_b32_e32 v132, v0
	s_nop 1
	v_permlane16_swap_b32_e32 v0, v132
	v_max_f32_e32 v0, v0, v132
	v_mov_b32_e32 v132, v0
	s_nop 1
	v_permlane32_swap_b32_e32 v0, v132
	ds_read_b128 v[98:101], v131 offset:53248
	v_max_f32_e32 v0, v0, v132
	s_mov_b32 s34, 0x41000000
	v_cmp_lt_f32_e32 vcc, s34, v0
	s_cmp_lg_u64 vcc, 0
	s_cselect_b64 s[34:35], -1, 0
	s_cbranch_vccz .Latt_B_1328
	v_cndmask_b32_e32 v132, 0, v0, vcc
	v_exp_f32_e64 v0, -v132
	v_sub_f32_e32 v160, v160, v132
	v_sub_f32_e32 v161, v161, v132
	v_sub_f32_e32 v162, v162, v132
	v_sub_f32_e32 v163, v163, v132
	v_sub_f32_e32 v164, v164, v132
	v_sub_f32_e32 v165, v165, v132
	v_sub_f32_e32 v166, v166, v132
	v_sub_f32_e32 v167, v167, v132
	v_sub_f32_e32 v168, v168, v132
	v_sub_f32_e32 v169, v169, v132
	v_sub_f32_e32 v170, v170, v132
	v_sub_f32_e32 v171, v171, v132
	v_sub_f32_e32 v172, v172, v132
	v_sub_f32_e32 v173, v173, v132
	v_sub_f32_e32 v174, v174, v132
	v_sub_f32_e32 v175, v175, v132
	v_add_f32_e32 v113, v113, v132
	v_xor_b32_e32 v150, 0x80000000, v113
	v_mov_b32_e32 v151, v150
	v_mov_b32_e32 v152, v150
	v_mov_b32_e32 v153, v150
	s_branch .Latt_B_1329
.Latt_B_1328:
.Latt_B_1329:
	ds_read_b128 v[134:137], v131 offset:55296
	s_waitcnt lgkmcnt(5)
	v_mfma_f32_16x16x32_bf16 v[22:25], v[78:81], v[18:21], v[90:93]
	ds_read_b128 v[78:81], v131 offset:57344
	s_waitcnt lgkmcnt(5)
	v_mfma_f32_16x16x32_bf16 v[26:29], v[86:89], v[18:21], v[94:97]
	ds_read_b128 v[86:89], v131 offset:59392
	s_waitcnt lgkmcnt(5)
	v_mfma_f32_16x16x32_bf16 v[30:33], v[82:85], v[14:17], v[30:33]
	v_exp_f32_e32 v145, v160
	v_exp_f32_e32 v146, v161
	v_exp_f32_e32 v147, v162
	v_exp_f32_e32 v148, v163
	ds_read_b128 v[176:179], v131 offset:61440
	s_waitcnt lgkmcnt(5)
	v_mfma_f32_16x16x32_bf16 v[50:53], v[102:105], v[14:17], v[50:53]
	ds_read_b128 v[82:85], v131 offset:63488
	s_waitcnt lgkmcnt(5)
	v_mfma_f32_16x16x32_bf16 v[42:45], v[98:101], v[14:17], v[42:45]
	ds_read_b128 v[90:93], v131 offset:50176
	s_waitcnt lgkmcnt(5)
	v_mfma_f32_16x16x32_bf16 v[34:37], v[134:137], v[14:17], v[34:37]
	v_exp_f32_e32 v98, v164
	v_exp_f32_e32 v99, v165
	v_exp_f32_e32 v100, v166
	v_exp_f32_e32 v101, v167
	ds_read_b128 v[180:183], v131 offset:52224
	s_waitcnt lgkmcnt(5)
	v_mfma_f32_16x16x32_bf16 v[58:61], v[78:81], v[14:17], v[58:61]
	ds_read_b128 v[78:81], v131 offset:54272
	s_waitcnt lgkmcnt(5)
	v_mfma_f32_16x16x32_bf16 v[54:57], v[86:89], v[14:17], v[54:57]
	ds_read_b128 v[86:89], v131 offset:56320
	s_waitcnt lgkmcnt(5)
	v_mfma_f32_16x16x32_bf16 v[46:49], v[176:179], v[14:17], v[46:49]
	v_exp_f32_e32 v102, v168
	v_exp_f32_e32 v103, v169
	v_exp_f32_e32 v104, v170
	v_exp_f32_e32 v105, v171
	ds_read_b128 v[176:179], v131 offset:58368
	s_waitcnt lgkmcnt(5)
	v_mfma_f32_16x16x32_bf16 v[38:41], v[82:85], v[14:17], v[38:41]
	v_mfma_f32_16x16x32_bf16 v[2:5], v[154:157], v[14:17], v[2:5]
	ds_read_b128 v[94:97], v131 offset:60416
	s_waitcnt lgkmcnt(5)
	v_mfma_f32_16x16x32_bf16 v[30:33], v[90:93], v[184:187], v[30:33]
	v_exp_f32_e32 v133, v172
	v_exp_f32_e32 v134, v173
	v_exp_f32_e32 v135, v174
	v_exp_f32_e32 v136, v175
	ds_read_b128 v[90:93], v131 offset:62464
	s_waitcnt lgkmcnt(5)
	v_mfma_f32_16x16x32_bf16 v[50:53], v[180:183], v[184:187], v[50:53]
	ds_read_b128 v[180:183], v131 offset:64512
	s_waitcnt lgkmcnt(5)
	v_mfma_f32_16x16x32_bf16 v[42:45], v[78:81], v[184:187], v[42:45]
	s_waitcnt lgkmcnt(4)
	v_mfma_f32_16x16x32_bf16 v[34:37], v[86:89], v[184:187], v[34:37]
	v_cvt_pk_bf16_f32 v14, v145, v146
	v_cvt_pk_bf16_f32 v15, v147, v148
	v_cvt_pk_bf16_f32 v16, v98, v99
	v_cvt_pk_bf16_f32 v17, v100, v101
	v_cvt_pk_bf16_f32 v6, v102, v103
	v_cvt_pk_bf16_f32 v7, v104, v105
	v_cvt_pk_bf16_f32 v8, v133, v134
	v_cvt_pk_bf16_f32 v9, v135, v136
	s_waitcnt lgkmcnt(3)
	v_mfma_f32_16x16x32_bf16 v[58:61], v[176:179], v[184:187], v[58:61]
	s_waitcnt lgkmcnt(2)
	v_mfma_f32_16x16x32_bf16 v[54:57], v[94:97], v[184:187], v[54:57]
	s_waitcnt lgkmcnt(1)
	v_mfma_f32_16x16x32_bf16 v[46:49], v[90:93], v[184:187], v[46:49]
	s_waitcnt lgkmcnt(0)
	v_mfma_f32_16x16x32_bf16 v[38:41], v[180:183], v[184:187], v[38:41]
	v_mfma_f32_16x16x32_bf16 v[2:5], v[154:157], v[184:187], v[2:5]
	s_andn2_b64 vcc, exec, s[34:35]
	s_cbranch_vccnz .Latt_B_1331
	v_sub_f32_e32 v74, v74, v132
	v_sub_f32_e32 v75, v75, v132
	v_sub_f32_e32 v76, v76, v132
	v_sub_f32_e32 v77, v77, v132
	v_sub_f32_e32 v70, v70, v132
	v_sub_f32_e32 v71, v71, v132
	v_sub_f32_e32 v72, v72, v132
	v_sub_f32_e32 v73, v73, v132
	v_sub_f32_e32 v22, v22, v132
	v_sub_f32_e32 v23, v23, v132
	v_sub_f32_e32 v24, v24, v132
	v_sub_f32_e32 v25, v25, v132
	v_sub_f32_e32 v26, v26, v132
	v_sub_f32_e32 v27, v27, v132
	v_sub_f32_e32 v28, v28, v132
	v_sub_f32_e32 v29, v29, v132
	v_pk_mul_f32 v[40:41], v[0:1], v[40:41] op_sel_hi:[0,1]
	v_pk_mul_f32 v[48:49], v[0:1], v[48:49] op_sel_hi:[0,1]
	v_pk_mul_f32 v[56:57], v[0:1], v[56:57] op_sel_hi:[0,1]
	v_pk_mul_f32 v[60:61], v[0:1], v[60:61] op_sel_hi:[0,1]
	v_pk_mul_f32 v[36:37], v[0:1], v[36:37] op_sel_hi:[0,1]
	v_pk_mul_f32 v[44:45], v[0:1], v[44:45] op_sel_hi:[0,1]
	v_pk_mul_f32 v[52:53], v[0:1], v[52:53] op_sel_hi:[0,1]
	v_pk_mul_f32 v[32:33], v[0:1], v[32:33] op_sel_hi:[0,1]
	v_pk_mul_f32 v[38:39], v[0:1], v[38:39] op_sel_hi:[0,1]
	v_pk_mul_f32 v[46:47], v[0:1], v[46:47] op_sel_hi:[0,1]
	v_pk_mul_f32 v[54:55], v[0:1], v[54:55] op_sel_hi:[0,1]
	v_pk_mul_f32 v[58:59], v[0:1], v[58:59] op_sel_hi:[0,1]
	v_pk_mul_f32 v[34:35], v[0:1], v[34:35] op_sel_hi:[0,1]
	v_pk_mul_f32 v[42:43], v[0:1], v[42:43] op_sel_hi:[0,1]
	v_pk_mul_f32 v[50:51], v[0:1], v[50:51] op_sel_hi:[0,1]
	v_pk_mul_f32 v[30:31], v[0:1], v[30:31] op_sel_hi:[0,1]
	v_pk_mul_f32 v[4:5], v[0:1], v[4:5] op_sel_hi:[0,1]
	v_pk_mul_f32 v[2:3], v[0:1], v[2:3] op_sel_hi:[0,1]

.Latt_exitA:
	v_mov_b64_e32 v[6:7], v[184:185]
	v_mov_b64_e32 v[8:9], v[186:187]
	s_branch .LBB0_1333
